# v23 + residual-GEMM row-sum xor-16 shuffle via permlane16_swap (no LDS bpermute left in that epilogue)
# baseline (speedup 1.0000x reference)
; #define PG8_GAS __attribute__((address_space(1)))
;     __device__ __forceinline__ void operator()(const f32x4 (&acc)[2][2][4][2], const Unit& u, int wr, int wc, int fr, int fq) const {
;         const int row0 = u.pm * BM + wr * 64 + fr; const int col0 = u.pn * BM + wc * 32 + 8 * fq;
;         PG8_GAS bf16_t* XBg = (PG8_GAS bf16_t*)XB; PG8_GAS unsigned long long* ssg = (PG8_GAS unsigned long long*)ss;
;         u32x4 pre[2][4][2];
; #pragma unroll
;         for (int ai = 0; ai < 2; ++ai)
; #pragma unroll
;             for (int m = 0; m < 4; ++m)
; #pragma unroll
;                 for (int bj = 0; bj < 2; ++bj) pre[ai][m][bj] = *(const PG8_GAS u32x4*)(XBg + (size_t)(row0 + ai * HALF + m * 16) * ldc + col0 + bj * HALF);
; #pragma unroll
;         for (int ai = 0; ai < 2; ++ai)
; #pragma unroll
;             for (int m = 0; m < 4; ++m) { const int row = row0 + ai * HALF + m * 16; PG8_GAS bf16_t* rowb = XBg + (size_t)row * ldc + col0;
;                 float sq = 0.f;
; #pragma unroll
;                 for (int bj = 0; bj < 2; ++bj) { const u32x4 o = pre[ai][m][bj]; const f32x4 c0 = acc[ai][bj][m][0], c1 = acc[ai][bj][m][1];
;                     u32x4 w; w.x = cvt_pk_bf16(__uint_as_float(o.x << 16) + c0[0], __uint_as_float(o.x & 0xffff0000u) + c0[1]); w.y = cvt_pk_bf16(__uint_as_float(o.y << 16) + c0[2], __uint_as_float(o.y & 0xffff0000u) + c0[3]);
;                     w.z = cvt_pk_bf16(__uint_as_float(o.z << 16) + c1[0], __uint_as_float(o.z & 0xffff0000u) + c1[1]); w.w = cvt_pk_bf16(__uint_as_float(o.w << 16) + c1[2], __uint_as_float(o.w & 0xffff0000u) + c1[3]);
;                     *(PG8_GAS u32x4*)(rowb + bj * HALF) = w;
;                     const float a0 = __uint_as_float(w.x << 16), a1 = __uint_as_float(w.x & 0xffff0000u), a2 = __uint_as_float(w.y << 16), a3 = __uint_as_float(w.y & 0xffff0000u);
;                     const float b0 = __uint_as_float(w.z << 16), b1 = __uint_as_float(w.z & 0xffff0000u), b2 = __uint_as_float(w.w << 16), b3 = __uint_as_float(w.w & 0xffff0000u);
;                     sq += (a0 * a0 + a1 * a1) + (a2 * a2 + a3 * a3) + (b0 * b0 + b1 * b1) + (b2 * b2 + b3 * b3); }
;                 sq += __shfl_xor(sq, 16); sq += __shfl_xor(sq, 32);
;                 if (fq == 0) __hip_atomic_fetch_add(ssg + row, (unsigned long long)(sq * 1048576.0f + 0.5f), __ATOMIC_RELAXED, __HIP_MEMORY_SCOPE_AGENT); }
.LBB0_383:
	v_lshl_add_u32 v222, s76, 8, v196
	v_lshl_or_b32 v124, s57, 8, v250
	v_ashrrev_i32_e32 v125, 31, v124
	v_ashrrev_i32_e32 v223, 31, v222
	v_lshl_add_u64 v[124:125], v[124:125], 1, s[14:15]
	v_lshlrev_b64 v[126:127], 11, v[222:223]
	v_lshl_add_u64 v[224:225], v[124:125], 0, v[126:127]
	global_load_dwordx4 v[188:191], v[224:225], off
	global_load_dwordx4 v[184:187], v[224:225], off offset:256
	v_or_b32_e32 v126, 16, v222
	v_ashrrev_i32_e32 v127, 31, v126
	v_lshlrev_b64 v[126:127], 11, v[126:127]
	v_lshl_add_u64 v[220:221], v[124:125], 0, v[126:127]
	v_or_b32_e32 v126, 32, v222
	v_ashrrev_i32_e32 v127, 31, v126
	v_lshlrev_b64 v[126:127], 11, v[126:127]
	v_lshl_add_u64 v[218:219], v[124:125], 0, v[126:127]
	v_or_b32_e32 v126, 48, v222
	v_ashrrev_i32_e32 v127, 31, v126
	s_mov_b64 s[40:41], 0x40000
	v_lshlrev_b64 v[126:127], 11, v[126:127]
	v_lshl_add_u64 v[214:215], v[224:225], 0, s[40:41]
	s_mov_b32 s40, 0x40000
	v_lshl_add_u64 v[216:217], v[124:125], 0, v[126:127]
	v_add_co_u32_e32 v124, vcc, s40, v224
	s_mov_b64 s[40:41], 0x48000
	s_nop 0
	v_addc_co_u32_e32 v125, vcc, 0, v225, vcc
	v_lshl_add_u64 v[212:213], v[224:225], 0, s[40:41]
	s_mov_b32 s40, 0x48000
	global_load_dwordx4 v[180:183], v[220:221], off
	global_load_dwordx4 v[176:179], v[220:221], off offset:256
	global_load_dwordx4 v[172:175], v[218:219], off
	global_load_dwordx4 v[168:171], v[218:219], off offset:256
	global_load_dwordx4 v[164:167], v[216:217], off
	global_load_dwordx4 v[156:159], v[216:217], off offset:256
	global_load_dwordx4 v[160:163], v[124:125], off
	global_load_dwordx4 v[152:155], v[214:215], off offset:256
	v_add_co_u32_e32 v124, vcc, s40, v224
	s_mov_b64 s[40:41], 0x50000
	s_nop 0
	v_addc_co_u32_e32 v125, vcc, 0, v225, vcc
	v_lshl_add_u64 v[210:211], v[224:225], 0, s[40:41]
	s_mov_b32 s40, 0x50000
	global_load_dwordx4 v[148:151], v[124:125], off
	global_load_dwordx4 v[144:147], v[212:213], off offset:256
	v_add_co_u32_e32 v124, vcc, s40, v224
	s_mov_b64 s[40:41], 0x58000
	s_nop 0
	v_addc_co_u32_e32 v125, vcc, 0, v225, vcc
	v_lshl_add_u64 v[208:209], v[224:225], 0, s[40:41]
	s_mov_b32 s40, 0x58000
	global_load_dwordx4 v[140:143], v[124:125], off
	global_load_dwordx4 v[128:131], v[210:211], off offset:256
	v_add_co_u32_e32 v124, vcc, s40, v224
	s_waitcnt vmcnt(0)
	v_lshlrev_b32_e32 v242, 16, v188
	v_addc_co_u32_e32 v125, vcc, 0, v225, vcc
	global_load_dwordx4 v[132:135], v[124:125], off
	s_nop 0
	global_load_dwordx4 v[124:127], v[208:209], off offset:256
	v_and_b32_e32 v188, 0xffff0000, v188
	v_add_f32_e32 v136, v136, v242
	v_add_f32_e32 v137, v137, v188
	v_cvt_pk_bf16_f32 v136, v136, v137
	v_lshlrev_b32_e32 v137, 16, v189
	v_add_f32_e32 v137, v138, v137
	v_and_b32_e32 v138, 0xffff0000, v189
	v_add_f32_e32 v138, v139, v138
	v_cvt_pk_bf16_f32 v137, v137, v138
	v_lshlrev_b32_e32 v138, 16, v190
	v_add_f32_e32 v120, v120, v138
	v_and_b32_e32 v138, 0xffff0000, v190
	v_add_f32_e32 v121, v121, v138
	v_cvt_pk_bf16_f32 v138, v120, v121
	v_and_b32_e32 v121, 0xffff0000, v191
	v_lshlrev_b32_e32 v120, 16, v191
	v_add_f32_e32 v121, v123, v121
	v_add_f32_e32 v120, v122, v120
	v_cvt_pk_bf16_f32 v139, v120, v121
	v_and_b32_e32 v121, 0xffff0000, v136
	v_lshlrev_b32_e32 v120, 16, v136
	v_and_b32_e32 v123, 0xffff0000, v137
	v_mul_f32_e32 v121, v121, v121
	v_lshlrev_b32_e32 v122, 16, v137
	v_fmac_f32_e32 v121, v120, v120
	v_mul_f32_e32 v120, v123, v123
	global_store_dwordx4 v[224:225], v[136:139], off
	v_fmac_f32_e32 v120, v122, v122
	v_add_f32_e32 v120, v121, v120
	v_and_b32_e32 v137, 0xffff0000, v138
	v_lshlrev_b32_e32 v136, 16, v138
	v_mul_f32_e32 v121, v137, v137
	v_lshlrev_b32_e32 v138, 16, v139
	v_and_b32_e32 v139, 0xffff0000, v139
	v_fmac_f32_e32 v121, v136, v136
	v_add_f32_e32 v120, v120, v121
	v_mul_f32_e32 v121, v139, v139
	v_fmac_f32_e32 v121, v138, v138
	v_add_f32_e32 v120, v120, v121
	v_lshlrev_b32_e32 v121, 16, v184
	v_add_f32_e32 v116, v116, v121
	v_and_b32_e32 v121, 0xffff0000, v184
	v_add_f32_e32 v117, v117, v121
	v_cvt_pk_bf16_f32 v116, v116, v117
	v_lshlrev_b32_e32 v117, 16, v185
	v_add_f32_e32 v117, v118, v117
	v_and_b32_e32 v118, 0xffff0000, v185
	v_add_f32_e32 v118, v119, v118
	v_cvt_pk_bf16_f32 v117, v117, v118
	v_lshlrev_b32_e32 v118, 16, v186
	v_add_f32_e32 v112, v112, v118
	v_and_b32_e32 v118, 0xffff0000, v186
	v_add_f32_e32 v113, v113, v118
	v_cvt_pk_bf16_f32 v118, v112, v113
	v_and_b32_e32 v113, 0xffff0000, v187
	v_lshlrev_b32_e32 v112, 16, v187
	v_add_f32_e32 v113, v115, v113
	v_add_f32_e32 v112, v114, v112
	v_cvt_pk_bf16_f32 v119, v112, v113
	v_and_b32_e32 v113, 0xffff0000, v116
	v_lshlrev_b32_e32 v112, 16, v116
	v_and_b32_e32 v115, 0xffff0000, v117
	v_mul_f32_e32 v113, v113, v113
	v_lshlrev_b32_e32 v114, 16, v117
	v_fmac_f32_e32 v113, v112, v112
	v_mul_f32_e32 v112, v115, v115
	global_store_dwordx4 v[224:225], v[116:119], off offset:256
	v_fmac_f32_e32 v112, v114, v114
	v_add_f32_e32 v112, v113, v112
	v_and_b32_e32 v117, 0xffff0000, v118
	v_lshlrev_b32_e32 v116, 16, v118
	v_mul_f32_e32 v113, v117, v117
	v_lshlrev_b32_e32 v118, 16, v119
	v_and_b32_e32 v119, 0xffff0000, v119
	v_fmac_f32_e32 v113, v116, v116
	v_add_f32_e32 v112, v112, v113
	v_mul_f32_e32 v113, v119, v119
	v_fmac_f32_e32 v113, v118, v118
	v_cmp_lt_i32_e32 vcc, v245, v240
	v_add_f32_e32 v112, v112, v113
	v_add_f32_e32 v112, v120, v112
	v_cndmask_b32_e32 v113, v239, v245, vcc
	v_lshlrev_b32_e32 v114, 2, v113
	v_mov_b32_e32 v113, v112
	s_nop 1
	v_permlane16_swap_b32_e32 v113, v112
	v_cmp_lt_i32_e32 vcc, v246, v240
	s_waitcnt lgkmcnt(0)
	v_add_f32_e32 v116, v112, v113
	v_cndmask_b32_e32 v112, v239, v246, vcc
	v_lshlrev_b32_e32 v115, 2, v112
	v_mov_b32_e32 v117, v116
	s_nop 1
	v_permlane32_swap_b32_e32 v117, v116
	v_lshl_add_u64 v[112:113], v[222:223], 3, s[54:55]
	s_and_saveexec_b64 s[40:41], s[38:39]
	s_cbranch_execz .LBB0_385
	s_waitcnt lgkmcnt(0)
	v_add_f32_e32 v116, v116, v117
	v_fma_f32 v116, v116, s80, 0.5
	v_trunc_f32_e32 v116, v116
	v_mul_f32_e32 v117, 0x2f800000, v116
	v_floor_f32_e32 v117, v117
	v_fmac_f32_e32 v116, 0xcf800000, v117
	v_cvt_u32_f32_e32 v116, v116
	v_cvt_u32_f32_e32 v117, v117
	global_atomic_add_x2 v[112:113], v[116:117], off
; #define PG8_GAS __attribute__((address_space(1)))
; __device__ __forceinline__ unsigned cvt_pk_bf16(float lo, float hi) { unsigned r; asm volatile("v_cvt_pk_bf16_f32 %0, %1, %2" : "=v"(r) : "v"(lo), "v"(hi)); return r; }
;     __device__ __forceinline__ void operator()(const f32x4 (&acc)[2][2][4][2], const Unit& u, int wr, int wc, int fr, int fq) const {
;     ...
;             for (int m = 0; m < 4; ++m) { const int row = row0 + ai * HALF + m * 16; PG8_GAS bf16_t* rowb = XBg + (size_t)row * ldc + col0;
;                 float sq = 0.f;
; #pragma unroll
;                 for (int bj = 0; bj < 2; ++bj) { const u32x4 o = pre[ai][m][bj]; const f32x4 c0 = acc[ai][bj][m][0], c1 = acc[ai][bj][m][1];
;                     u32x4 w; w.x = cvt_pk_bf16(__uint_as_float(o.x << 16) + c0[0], __uint_as_float(o.x & 0xffff0000u) + c0[1]); w.y = cvt_pk_bf16(__uint_as_float(o.y << 16) + c0[2], __uint_as_float(o.y & 0xffff0000u) + c0[3]);
;                     w.z = cvt_pk_bf16(__uint_as_float(o.z << 16) + c1[0], __uint_as_float(o.z & 0xffff0000u) + c1[1]); w.w = cvt_pk_bf16(__uint_as_float(o.w << 16) + c1[2], __uint_as_float(o.w & 0xffff0000u) + c1[3]);
;                     *(PG8_GAS u32x4*)(rowb + bj * HALF) = w;
;                     const float a0 = __uint_as_float(w.x << 16), a1 = __uint_as_float(w.x & 0xffff0000u), a2 = __uint_as_float(w.y << 16), a3 = __uint_as_float(w.y & 0xffff0000u);
;                     const float b0 = __uint_as_float(w.z << 16), b1 = __uint_as_float(w.z & 0xffff0000u), b2 = __uint_as_float(w.w << 16), b3 = __uint_as_float(w.w & 0xffff0000u);
;                     sq += (a0 * a0 + a1 * a1) + (a2 * a2 + a3 * a3) + (b0 * b0 + b1 * b1) + (b2 * b2 + b3 * b3); }
;                 sq += __shfl_xor(sq, 16); sq += __shfl_xor(sq, 32);
;                 if (fq == 0) __hip_atomic_fetch_add(ssg + row, (unsigned long long)(sq * 1048576.0f + 0.5f), __ATOMIC_RELAXED, __HIP_MEMORY_SCOPE_AGENT); }
.LBB0_385:
	s_or_b64 exec, exec, s[40:41]
	v_lshlrev_b32_e32 v116, 16, v180
	v_add_f32_e32 v108, v108, v116
	v_and_b32_e32 v116, 0xffff0000, v180
	v_add_f32_e32 v109, v109, v116
	v_cvt_pk_bf16_f32 v108, v108, v109
	v_lshlrev_b32_e32 v109, 16, v181
	v_add_f32_e32 v109, v110, v109
	v_and_b32_e32 v110, 0xffff0000, v181
	v_add_f32_e32 v110, v111, v110
	v_cvt_pk_bf16_f32 v109, v109, v110
	v_lshlrev_b32_e32 v110, 16, v182
	v_add_f32_e32 v104, v104, v110
	v_and_b32_e32 v110, 0xffff0000, v182
	v_add_f32_e32 v105, v105, v110
	v_cvt_pk_bf16_f32 v110, v104, v105
	v_and_b32_e32 v105, 0xffff0000, v183
	v_lshlrev_b32_e32 v104, 16, v183
	v_add_f32_e32 v105, v107, v105
	v_add_f32_e32 v104, v106, v104
	v_cvt_pk_bf16_f32 v111, v104, v105
	v_and_b32_e32 v105, 0xffff0000, v108
	v_lshlrev_b32_e32 v104, 16, v108
	v_and_b32_e32 v107, 0xffff0000, v109
	v_mul_f32_e32 v105, v105, v105
	v_lshlrev_b32_e32 v106, 16, v109
	v_fmac_f32_e32 v105, v104, v104
	v_mul_f32_e32 v104, v107, v107
	global_store_dwordx4 v[220:221], v[108:111], off
	v_fmac_f32_e32 v104, v106, v106
	v_add_f32_e32 v104, v105, v104
	v_and_b32_e32 v109, 0xffff0000, v110
	v_lshlrev_b32_e32 v108, 16, v110
	v_mul_f32_e32 v105, v109, v109
	v_lshlrev_b32_e32 v110, 16, v111
	v_and_b32_e32 v111, 0xffff0000, v111
	v_fmac_f32_e32 v105, v108, v108
	v_add_f32_e32 v104, v104, v105
	v_mul_f32_e32 v105, v111, v111
	v_fmac_f32_e32 v105, v110, v110
	v_add_f32_e32 v104, v104, v105
	v_lshlrev_b32_e32 v105, 16, v176
	v_add_f32_e32 v100, v100, v105
	v_and_b32_e32 v105, 0xffff0000, v176
	v_add_f32_e32 v101, v101, v105
	v_cvt_pk_bf16_f32 v100, v100, v101
	v_lshlrev_b32_e32 v101, 16, v177
	v_add_f32_e32 v101, v102, v101
	v_and_b32_e32 v102, 0xffff0000, v177
	v_add_f32_e32 v102, v103, v102
	v_cvt_pk_bf16_f32 v101, v101, v102
	v_lshlrev_b32_e32 v102, 16, v178
	v_add_f32_e32 v96, v96, v102
	v_and_b32_e32 v102, 0xffff0000, v178
	v_add_f32_e32 v97, v97, v102
	v_cvt_pk_bf16_f32 v102, v96, v97
	v_and_b32_e32 v97, 0xffff0000, v179
	v_lshlrev_b32_e32 v96, 16, v179
	v_add_f32_e32 v97, v99, v97
	v_add_f32_e32 v96, v98, v96
	v_cvt_pk_bf16_f32 v103, v96, v97
	v_and_b32_e32 v97, 0xffff0000, v100
	v_lshlrev_b32_e32 v96, 16, v100
	v_and_b32_e32 v99, 0xffff0000, v101
	v_mul_f32_e32 v97, v97, v97
	v_lshlrev_b32_e32 v98, 16, v101
	v_fmac_f32_e32 v97, v96, v96
	v_mul_f32_e32 v96, v99, v99
	v_and_b32_e32 v106, 0xffff0000, v102
	v_fmac_f32_e32 v96, v98, v98
	v_lshlrev_b32_e32 v105, 16, v102
	v_add_f32_e32 v96, v97, v96
	v_mul_f32_e32 v97, v106, v106
	v_and_b32_e32 v108, 0xffff0000, v103
	v_fmac_f32_e32 v97, v105, v105
	v_lshlrev_b32_e32 v107, 16, v103
	v_add_f32_e32 v96, v96, v97
	v_mul_f32_e32 v97, v108, v108
	v_fmac_f32_e32 v97, v107, v107
	v_add_f32_e32 v96, v96, v97
	v_add_f32_e32 v96, v104, v96
	v_mov_b32_e32 v97, v96
	s_nop 1
	v_permlane16_swap_b32_e32 v97, v96
	global_store_dwordx4 v[220:221], v[100:103], off offset:256
	s_waitcnt lgkmcnt(0)
	v_add_f32_e32 v96, v96, v97
	v_mov_b32_e32 v97, v96
	s_nop 1
	v_permlane32_swap_b32_e32 v97, v96
	s_and_saveexec_b64 s[40:41], s[38:39]
	s_cbranch_execz .LBB0_387
	s_waitcnt lgkmcnt(0)
	v_add_f32_e32 v96, v96, v97
	v_fma_f32 v96, v96, s80, 0.5
	v_trunc_f32_e32 v96, v96
	v_mul_f32_e32 v97, 0x2f800000, v96
	v_floor_f32_e32 v97, v97
	v_fmac_f32_e32 v96, 0xcf800000, v97
	v_cvt_u32_f32_e32 v96, v96
	v_cvt_u32_f32_e32 v97, v97
	global_atomic_add_x2 v[112:113], v[96:97], off offset:128
.LBB0_387:
	s_or_b64 exec, exec, s[40:41]
	v_lshlrev_b32_e32 v96, 16, v172
	v_add_f32_e32 v92, v92, v96
	v_and_b32_e32 v96, 0xffff0000, v172
	v_add_f32_e32 v93, v93, v96
	v_cvt_pk_bf16_f32 v92, v92, v93
	v_lshlrev_b32_e32 v93, 16, v173
	v_add_f32_e32 v93, v94, v93
	v_and_b32_e32 v94, 0xffff0000, v173
	v_add_f32_e32 v94, v95, v94
	v_cvt_pk_bf16_f32 v93, v93, v94
	v_lshlrev_b32_e32 v94, 16, v174
	v_add_f32_e32 v88, v88, v94
	v_and_b32_e32 v94, 0xffff0000, v174
	v_add_f32_e32 v89, v89, v94
	v_cvt_pk_bf16_f32 v94, v88, v89
	v_and_b32_e32 v89, 0xffff0000, v175
	v_lshlrev_b32_e32 v88, 16, v175
	v_add_f32_e32 v89, v91, v89
	v_add_f32_e32 v88, v90, v88
	v_cvt_pk_bf16_f32 v95, v88, v89
	v_and_b32_e32 v89, 0xffff0000, v92
	v_lshlrev_b32_e32 v88, 16, v92
	v_and_b32_e32 v91, 0xffff0000, v93
	v_mul_f32_e32 v89, v89, v89
	v_lshlrev_b32_e32 v90, 16, v93
	v_fmac_f32_e32 v89, v88, v88
	v_mul_f32_e32 v88, v91, v91
	global_store_dwordx4 v[218:219], v[92:95], off
	v_fmac_f32_e32 v88, v90, v90
	v_add_f32_e32 v88, v89, v88
	v_and_b32_e32 v93, 0xffff0000, v94
	v_lshlrev_b32_e32 v92, 16, v94
	v_mul_f32_e32 v89, v93, v93
	v_lshlrev_b32_e32 v94, 16, v95
	v_and_b32_e32 v95, 0xffff0000, v95
	v_fmac_f32_e32 v89, v92, v92
	v_add_f32_e32 v88, v88, v89
	v_mul_f32_e32 v89, v95, v95
	v_fmac_f32_e32 v89, v94, v94
	v_add_f32_e32 v88, v88, v89
	v_lshlrev_b32_e32 v89, 16, v168
	v_add_f32_e32 v84, v84, v89
	v_and_b32_e32 v89, 0xffff0000, v168
	v_add_f32_e32 v85, v85, v89
	v_cvt_pk_bf16_f32 v84, v84, v85
	v_lshlrev_b32_e32 v85, 16, v169
	v_add_f32_e32 v85, v86, v85
	v_and_b32_e32 v86, 0xffff0000, v169
	v_add_f32_e32 v86, v87, v86
	v_cvt_pk_bf16_f32 v85, v85, v86
	v_lshlrev_b32_e32 v86, 16, v170
	v_add_f32_e32 v80, v80, v86
	v_and_b32_e32 v86, 0xffff0000, v170
	v_add_f32_e32 v81, v81, v86
	v_cvt_pk_bf16_f32 v86, v80, v81
	v_and_b32_e32 v81, 0xffff0000, v171
	v_lshlrev_b32_e32 v80, 16, v171
	v_add_f32_e32 v81, v83, v81
	v_add_f32_e32 v80, v82, v80
	v_cvt_pk_bf16_f32 v87, v80, v81
	v_and_b32_e32 v81, 0xffff0000, v84
	v_lshlrev_b32_e32 v80, 16, v84
	v_and_b32_e32 v83, 0xffff0000, v85
	v_mul_f32_e32 v81, v81, v81
	v_lshlrev_b32_e32 v82, 16, v85
	v_fmac_f32_e32 v81, v80, v80
	v_mul_f32_e32 v80, v83, v83
	v_and_b32_e32 v90, 0xffff0000, v86
	v_fmac_f32_e32 v80, v82, v82
	v_lshlrev_b32_e32 v89, 16, v86
	v_add_f32_e32 v80, v81, v80
	v_mul_f32_e32 v81, v90, v90
	v_and_b32_e32 v92, 0xffff0000, v87
	v_fmac_f32_e32 v81, v89, v89
	v_lshlrev_b32_e32 v91, 16, v87
	v_add_f32_e32 v80, v80, v81
	v_mul_f32_e32 v81, v92, v92
	v_fmac_f32_e32 v81, v91, v91
	v_add_f32_e32 v80, v80, v81
	v_add_f32_e32 v80, v88, v80
	v_mov_b32_e32 v81, v80
	s_nop 1
	v_permlane16_swap_b32_e32 v81, v80
	global_store_dwordx4 v[218:219], v[84:87], off offset:256
	s_waitcnt lgkmcnt(0)
	v_add_f32_e32 v80, v80, v81
	v_mov_b32_e32 v81, v80
	s_nop 1
	v_permlane32_swap_b32_e32 v81, v80
	s_and_saveexec_b64 s[40:41], s[38:39]
	s_cbranch_execz .LBB0_389
	s_waitcnt lgkmcnt(0)
	v_add_f32_e32 v80, v80, v81
	v_fma_f32 v80, v80, s80, 0.5
	v_trunc_f32_e32 v80, v80
	v_mul_f32_e32 v81, 0x2f800000, v80
	v_floor_f32_e32 v81, v81
	v_fmac_f32_e32 v80, 0xcf800000, v81
	v_cvt_u32_f32_e32 v80, v80
	v_cvt_u32_f32_e32 v81, v81
	global_atomic_add_x2 v[112:113], v[80:81], off offset:256
; #define PG8_GAS __attribute__((address_space(1)))
; __device__ __forceinline__ unsigned cvt_pk_bf16(float lo, float hi) { unsigned r; asm volatile("v_cvt_pk_bf16_f32 %0, %1, %2" : "=v"(r) : "v"(lo), "v"(hi)); return r; }
;     __device__ __forceinline__ void operator()(const f32x4 (&acc)[2][2][4][2], const Unit& u, int wr, int wc, int fr, int fq) const {
;     ...
;             for (int m = 0; m < 4; ++m) { const int row = row0 + ai * HALF + m * 16; PG8_GAS bf16_t* rowb = XBg + (size_t)row * ldc + col0;
;                 float sq = 0.f;
; #pragma unroll
;                 for (int bj = 0; bj < 2; ++bj) { const u32x4 o = pre[ai][m][bj]; const f32x4 c0 = acc[ai][bj][m][0], c1 = acc[ai][bj][m][1];
;                     u32x4 w; w.x = cvt_pk_bf16(__uint_as_float(o.x << 16) + c0[0], __uint_as_float(o.x & 0xffff0000u) + c0[1]); w.y = cvt_pk_bf16(__uint_as_float(o.y << 16) + c0[2], __uint_as_float(o.y & 0xffff0000u) + c0[3]);
;                     w.z = cvt_pk_bf16(__uint_as_float(o.z << 16) + c1[0], __uint_as_float(o.z & 0xffff0000u) + c1[1]); w.w = cvt_pk_bf16(__uint_as_float(o.w << 16) + c1[2], __uint_as_float(o.w & 0xffff0000u) + c1[3]);
;                     *(PG8_GAS u32x4*)(rowb + bj * HALF) = w;
;                     const float a0 = __uint_as_float(w.x << 16), a1 = __uint_as_float(w.x & 0xffff0000u), a2 = __uint_as_float(w.y << 16), a3 = __uint_as_float(w.y & 0xffff0000u);
;                     const float b0 = __uint_as_float(w.z << 16), b1 = __uint_as_float(w.z & 0xffff0000u), b2 = __uint_as_float(w.w << 16), b3 = __uint_as_float(w.w & 0xffff0000u);
;                     sq += (a0 * a0 + a1 * a1) + (a2 * a2 + a3 * a3) + (b0 * b0 + b1 * b1) + (b2 * b2 + b3 * b3); }
;                 sq += __shfl_xor(sq, 16); sq += __shfl_xor(sq, 32);
;                 if (fq == 0) __hip_atomic_fetch_add(ssg + row, (unsigned long long)(sq * 1048576.0f + 0.5f), __ATOMIC_RELAXED, __HIP_MEMORY_SCOPE_AGENT); }
.LBB0_389:
	s_or_b64 exec, exec, s[40:41]
	v_lshlrev_b32_e32 v80, 16, v164
	v_add_f32_e32 v76, v76, v80
	v_and_b32_e32 v80, 0xffff0000, v164
	v_add_f32_e32 v77, v77, v80
	v_cvt_pk_bf16_f32 v76, v76, v77
	v_lshlrev_b32_e32 v77, 16, v165
	v_add_f32_e32 v77, v78, v77
	v_and_b32_e32 v78, 0xffff0000, v165
	v_add_f32_e32 v78, v79, v78
	v_cvt_pk_bf16_f32 v77, v77, v78
	v_lshlrev_b32_e32 v78, 16, v166
	v_add_f32_e32 v72, v72, v78
	v_and_b32_e32 v78, 0xffff0000, v166
	v_add_f32_e32 v73, v73, v78
	v_cvt_pk_bf16_f32 v78, v72, v73
	v_and_b32_e32 v73, 0xffff0000, v167
	v_lshlrev_b32_e32 v72, 16, v167
	v_add_f32_e32 v73, v75, v73
	v_add_f32_e32 v72, v74, v72
	v_cvt_pk_bf16_f32 v79, v72, v73
	v_and_b32_e32 v73, 0xffff0000, v76
	v_lshlrev_b32_e32 v72, 16, v76
	v_and_b32_e32 v75, 0xffff0000, v77
	v_mul_f32_e32 v73, v73, v73
	v_lshlrev_b32_e32 v74, 16, v77
	v_fmac_f32_e32 v73, v72, v72
	v_mul_f32_e32 v72, v75, v75
	global_store_dwordx4 v[216:217], v[76:79], off
	v_fmac_f32_e32 v72, v74, v74
	v_add_f32_e32 v72, v73, v72
	v_and_b32_e32 v77, 0xffff0000, v78
	v_lshlrev_b32_e32 v76, 16, v78
	v_mul_f32_e32 v73, v77, v77
	v_lshlrev_b32_e32 v78, 16, v79
	v_and_b32_e32 v79, 0xffff0000, v79
	v_fmac_f32_e32 v73, v76, v76
	v_add_f32_e32 v72, v72, v73
	v_mul_f32_e32 v73, v79, v79
	v_fmac_f32_e32 v73, v78, v78
	v_add_f32_e32 v72, v72, v73
	v_lshlrev_b32_e32 v73, 16, v156
	v_add_f32_e32 v68, v68, v73
	v_and_b32_e32 v73, 0xffff0000, v156
	v_add_f32_e32 v69, v69, v73
	v_cvt_pk_bf16_f32 v68, v68, v69
	v_lshlrev_b32_e32 v69, 16, v157
	v_add_f32_e32 v69, v70, v69
	v_and_b32_e32 v70, 0xffff0000, v157
	v_add_f32_e32 v70, v71, v70
	v_cvt_pk_bf16_f32 v69, v69, v70
	v_lshlrev_b32_e32 v70, 16, v158
	v_add_f32_e32 v64, v64, v70
	v_and_b32_e32 v70, 0xffff0000, v158
	v_add_f32_e32 v65, v65, v70
	v_cvt_pk_bf16_f32 v70, v64, v65
	v_and_b32_e32 v65, 0xffff0000, v159
	v_lshlrev_b32_e32 v64, 16, v159
	v_add_f32_e32 v65, v67, v65
	v_add_f32_e32 v64, v66, v64
	v_cvt_pk_bf16_f32 v71, v64, v65
	v_and_b32_e32 v65, 0xffff0000, v68
	v_lshlrev_b32_e32 v64, 16, v68
	v_and_b32_e32 v67, 0xffff0000, v69
	v_mul_f32_e32 v65, v65, v65
	v_lshlrev_b32_e32 v66, 16, v69
	v_fmac_f32_e32 v65, v64, v64
	v_mul_f32_e32 v64, v67, v67
	v_and_b32_e32 v74, 0xffff0000, v70
	v_fmac_f32_e32 v64, v66, v66
	v_lshlrev_b32_e32 v73, 16, v70
	v_add_f32_e32 v64, v65, v64
	v_mul_f32_e32 v65, v74, v74
	v_and_b32_e32 v76, 0xffff0000, v71
	v_fmac_f32_e32 v65, v73, v73
	v_lshlrev_b32_e32 v75, 16, v71
	v_add_f32_e32 v64, v64, v65
	v_mul_f32_e32 v65, v76, v76
	v_fmac_f32_e32 v65, v75, v75
	v_add_f32_e32 v64, v64, v65
	v_add_f32_e32 v64, v72, v64
	v_mov_b32_e32 v65, v64
	s_nop 1
	v_permlane16_swap_b32_e32 v65, v64
	global_store_dwordx4 v[216:217], v[68:71], off offset:256
	s_waitcnt lgkmcnt(0)
	v_add_f32_e32 v64, v64, v65
	v_mov_b32_e32 v65, v64
	s_nop 1
	v_permlane32_swap_b32_e32 v65, v64
	s_and_saveexec_b64 s[40:41], s[38:39]
	s_cbranch_execz .LBB0_391
	s_waitcnt lgkmcnt(0)
	v_add_f32_e32 v64, v64, v65
	v_fma_f32 v64, v64, s80, 0.5
	v_trunc_f32_e32 v64, v64
	v_mul_f32_e32 v65, 0x2f800000, v64
	v_floor_f32_e32 v65, v65
	v_fmac_f32_e32 v64, 0xcf800000, v65
	v_cvt_u32_f32_e32 v64, v64
	v_cvt_u32_f32_e32 v65, v65
	global_atomic_add_x2 v[112:113], v[64:65], off offset:384
.LBB0_391:
	s_or_b64 exec, exec, s[40:41]
	v_lshlrev_b32_e32 v64, 16, v160
	v_add_f32_e32 v60, v60, v64
	v_and_b32_e32 v64, 0xffff0000, v160
	v_add_f32_e32 v61, v61, v64
	v_cvt_pk_bf16_f32 v60, v60, v61
	v_lshlrev_b32_e32 v61, 16, v161
	v_add_f32_e32 v61, v62, v61
	v_and_b32_e32 v62, 0xffff0000, v161
	v_add_f32_e32 v62, v63, v62
	v_cvt_pk_bf16_f32 v61, v61, v62
	v_lshlrev_b32_e32 v62, 16, v162
	v_add_f32_e32 v56, v56, v62
	v_and_b32_e32 v62, 0xffff0000, v162
	v_add_f32_e32 v57, v57, v62
	v_cvt_pk_bf16_f32 v62, v56, v57
	v_and_b32_e32 v57, 0xffff0000, v163
	v_lshlrev_b32_e32 v56, 16, v163
	v_add_f32_e32 v57, v59, v57
	v_add_f32_e32 v56, v58, v56
	v_cvt_pk_bf16_f32 v63, v56, v57
	v_and_b32_e32 v57, 0xffff0000, v60
	v_lshlrev_b32_e32 v56, 16, v60
	v_and_b32_e32 v59, 0xffff0000, v61
	v_mul_f32_e32 v57, v57, v57
	v_lshlrev_b32_e32 v58, 16, v61
	v_fmac_f32_e32 v57, v56, v56
	v_mul_f32_e32 v56, v59, v59
	global_store_dwordx4 v[214:215], v[60:63], off
	v_fmac_f32_e32 v56, v58, v58
	v_add_f32_e32 v56, v57, v56
	v_and_b32_e32 v61, 0xffff0000, v62
	v_lshlrev_b32_e32 v60, 16, v62
	v_mul_f32_e32 v57, v61, v61
	v_lshlrev_b32_e32 v62, 16, v63
	v_and_b32_e32 v63, 0xffff0000, v63
	v_fmac_f32_e32 v57, v60, v60
	v_add_f32_e32 v56, v56, v57
	v_mul_f32_e32 v57, v63, v63
	v_fmac_f32_e32 v57, v62, v62
	v_add_f32_e32 v56, v56, v57
	v_lshlrev_b32_e32 v57, 16, v152
	v_add_f32_e32 v52, v52, v57
	v_and_b32_e32 v57, 0xffff0000, v152
	v_add_f32_e32 v53, v53, v57
	v_cvt_pk_bf16_f32 v52, v52, v53
	v_lshlrev_b32_e32 v53, 16, v153
	v_add_f32_e32 v53, v54, v53
	v_and_b32_e32 v54, 0xffff0000, v153
	v_add_f32_e32 v54, v55, v54
	v_cvt_pk_bf16_f32 v53, v53, v54
	v_lshlrev_b32_e32 v54, 16, v154
	v_add_f32_e32 v48, v48, v54
	v_and_b32_e32 v54, 0xffff0000, v154
	v_add_f32_e32 v49, v49, v54
	v_cvt_pk_bf16_f32 v54, v48, v49
	v_and_b32_e32 v49, 0xffff0000, v155
	v_lshlrev_b32_e32 v48, 16, v155
	v_add_f32_e32 v49, v51, v49
	v_add_f32_e32 v48, v50, v48
	v_cvt_pk_bf16_f32 v55, v48, v49
	v_and_b32_e32 v49, 0xffff0000, v52
	v_lshlrev_b32_e32 v48, 16, v52
	v_and_b32_e32 v51, 0xffff0000, v53
	v_mul_f32_e32 v49, v49, v49
	v_lshlrev_b32_e32 v50, 16, v53
	v_fmac_f32_e32 v49, v48, v48
	v_mul_f32_e32 v48, v51, v51
	v_and_b32_e32 v58, 0xffff0000, v54
	v_fmac_f32_e32 v48, v50, v50
	v_lshlrev_b32_e32 v57, 16, v54
	v_add_f32_e32 v48, v49, v48
	v_mul_f32_e32 v49, v58, v58
	v_and_b32_e32 v60, 0xffff0000, v55
	v_fmac_f32_e32 v49, v57, v57
	v_lshlrev_b32_e32 v59, 16, v55
	v_add_f32_e32 v48, v48, v49
	v_mul_f32_e32 v49, v60, v60
	v_fmac_f32_e32 v49, v59, v59
	v_add_f32_e32 v48, v48, v49
	v_add_f32_e32 v48, v56, v48
	v_mov_b32_e32 v49, v48
	s_nop 1
	v_permlane16_swap_b32_e32 v49, v48
	global_store_dwordx4 v[214:215], v[52:55], off offset:256
	s_waitcnt lgkmcnt(0)
	v_add_f32_e32 v48, v48, v49
	v_mov_b32_e32 v49, v48
	s_nop 1
	v_permlane32_swap_b32_e32 v49, v48
	s_and_saveexec_b64 s[40:41], s[38:39]
	s_cbranch_execz .LBB0_393
	s_waitcnt lgkmcnt(0)
	v_add_f32_e32 v48, v48, v49
	v_fma_f32 v48, v48, s80, 0.5
	v_trunc_f32_e32 v48, v48
	v_mul_f32_e32 v49, 0x2f800000, v48
	v_floor_f32_e32 v49, v49
	v_fmac_f32_e32 v48, 0xcf800000, v49
	v_cvt_u32_f32_e32 v48, v48
	v_cvt_u32_f32_e32 v49, v49
	global_atomic_add_x2 v[112:113], v[48:49], off offset:1024
; #define PG8_GAS __attribute__((address_space(1)))
; __device__ __forceinline__ unsigned cvt_pk_bf16(float lo, float hi) { unsigned r; asm volatile("v_cvt_pk_bf16_f32 %0, %1, %2" : "=v"(r) : "v"(lo), "v"(hi)); return r; }
;     __device__ __forceinline__ void operator()(const f32x4 (&acc)[2][2][4][2], const Unit& u, int wr, int wc, int fr, int fq) const {
;     ...
;             for (int m = 0; m < 4; ++m) { const int row = row0 + ai * HALF + m * 16; PG8_GAS bf16_t* rowb = XBg + (size_t)row * ldc + col0;
;                 float sq = 0.f;
; #pragma unroll
;                 for (int bj = 0; bj < 2; ++bj) { const u32x4 o = pre[ai][m][bj]; const f32x4 c0 = acc[ai][bj][m][0], c1 = acc[ai][bj][m][1];
;                     u32x4 w; w.x = cvt_pk_bf16(__uint_as_float(o.x << 16) + c0[0], __uint_as_float(o.x & 0xffff0000u) + c0[1]); w.y = cvt_pk_bf16(__uint_as_float(o.y << 16) + c0[2], __uint_as_float(o.y & 0xffff0000u) + c0[3]);
;                     w.z = cvt_pk_bf16(__uint_as_float(o.z << 16) + c1[0], __uint_as_float(o.z & 0xffff0000u) + c1[1]); w.w = cvt_pk_bf16(__uint_as_float(o.w << 16) + c1[2], __uint_as_float(o.w & 0xffff0000u) + c1[3]);
;                     *(PG8_GAS u32x4*)(rowb + bj * HALF) = w;
;                     const float a0 = __uint_as_float(w.x << 16), a1 = __uint_as_float(w.x & 0xffff0000u), a2 = __uint_as_float(w.y << 16), a3 = __uint_as_float(w.y & 0xffff0000u);
;                     const float b0 = __uint_as_float(w.z << 16), b1 = __uint_as_float(w.z & 0xffff0000u), b2 = __uint_as_float(w.w << 16), b3 = __uint_as_float(w.w & 0xffff0000u);
;                     sq += (a0 * a0 + a1 * a1) + (a2 * a2 + a3 * a3) + (b0 * b0 + b1 * b1) + (b2 * b2 + b3 * b3); }
;                 sq += __shfl_xor(sq, 16); sq += __shfl_xor(sq, 32);
;                 if (fq == 0) __hip_atomic_fetch_add(ssg + row, (unsigned long long)(sq * 1048576.0f + 0.5f), __ATOMIC_RELAXED, __HIP_MEMORY_SCOPE_AGENT); }
.LBB0_393:
	s_or_b64 exec, exec, s[40:41]
	v_lshlrev_b32_e32 v48, 16, v148
	v_add_f32_e32 v44, v44, v48
	v_and_b32_e32 v48, 0xffff0000, v148
	v_add_f32_e32 v45, v45, v48
	v_cvt_pk_bf16_f32 v44, v44, v45
	v_lshlrev_b32_e32 v45, 16, v149
	v_add_f32_e32 v45, v46, v45
	v_and_b32_e32 v46, 0xffff0000, v149
	v_add_f32_e32 v46, v47, v46
	v_cvt_pk_bf16_f32 v45, v45, v46
	v_lshlrev_b32_e32 v46, 16, v150
	v_add_f32_e32 v40, v40, v46
	v_and_b32_e32 v46, 0xffff0000, v150
	v_add_f32_e32 v41, v41, v46
	v_cvt_pk_bf16_f32 v46, v40, v41
	v_and_b32_e32 v41, 0xffff0000, v151
	v_lshlrev_b32_e32 v40, 16, v151
	v_add_f32_e32 v41, v43, v41
	v_add_f32_e32 v40, v42, v40
	v_cvt_pk_bf16_f32 v47, v40, v41
	v_and_b32_e32 v41, 0xffff0000, v44
	v_lshlrev_b32_e32 v40, 16, v44
	v_and_b32_e32 v43, 0xffff0000, v45
	v_mul_f32_e32 v41, v41, v41
	v_lshlrev_b32_e32 v42, 16, v45
	v_fmac_f32_e32 v41, v40, v40
	v_mul_f32_e32 v40, v43, v43
	global_store_dwordx4 v[212:213], v[44:47], off
	v_fmac_f32_e32 v40, v42, v42
	v_add_f32_e32 v40, v41, v40
	v_and_b32_e32 v45, 0xffff0000, v46
	v_lshlrev_b32_e32 v44, 16, v46
	v_mul_f32_e32 v41, v45, v45
	v_lshlrev_b32_e32 v46, 16, v47
	v_and_b32_e32 v47, 0xffff0000, v47
	v_fmac_f32_e32 v41, v44, v44
	v_add_f32_e32 v40, v40, v41
	v_mul_f32_e32 v41, v47, v47
	v_fmac_f32_e32 v41, v46, v46
	v_add_f32_e32 v40, v40, v41
	v_lshlrev_b32_e32 v41, 16, v144
	v_add_f32_e32 v36, v36, v41
	v_and_b32_e32 v41, 0xffff0000, v144
	v_add_f32_e32 v37, v37, v41
	v_cvt_pk_bf16_f32 v36, v36, v37
	v_lshlrev_b32_e32 v37, 16, v145
	v_add_f32_e32 v37, v38, v37
	v_and_b32_e32 v38, 0xffff0000, v145
	v_add_f32_e32 v38, v39, v38
	v_cvt_pk_bf16_f32 v37, v37, v38
	v_lshlrev_b32_e32 v38, 16, v146
	v_add_f32_e32 v32, v32, v38
	v_and_b32_e32 v38, 0xffff0000, v146
	v_add_f32_e32 v33, v33, v38
	v_cvt_pk_bf16_f32 v38, v32, v33
	v_and_b32_e32 v33, 0xffff0000, v147
	v_lshlrev_b32_e32 v32, 16, v147
	v_add_f32_e32 v33, v35, v33
	v_add_f32_e32 v32, v34, v32
	v_cvt_pk_bf16_f32 v39, v32, v33
	v_and_b32_e32 v33, 0xffff0000, v36
	v_lshlrev_b32_e32 v32, 16, v36
	v_and_b32_e32 v35, 0xffff0000, v37
	v_mul_f32_e32 v33, v33, v33
	v_lshlrev_b32_e32 v34, 16, v37
	v_fmac_f32_e32 v33, v32, v32
	v_mul_f32_e32 v32, v35, v35
	v_and_b32_e32 v42, 0xffff0000, v38
	v_fmac_f32_e32 v32, v34, v34
	v_lshlrev_b32_e32 v41, 16, v38
	v_add_f32_e32 v32, v33, v32
	v_mul_f32_e32 v33, v42, v42
	v_and_b32_e32 v44, 0xffff0000, v39
	v_fmac_f32_e32 v33, v41, v41
	v_lshlrev_b32_e32 v43, 16, v39
	v_add_f32_e32 v32, v32, v33
	v_mul_f32_e32 v33, v44, v44
	v_fmac_f32_e32 v33, v43, v43
	v_add_f32_e32 v32, v32, v33
	v_add_f32_e32 v32, v40, v32
	v_mov_b32_e32 v33, v32
	s_nop 1
	v_permlane16_swap_b32_e32 v33, v32
	global_store_dwordx4 v[212:213], v[36:39], off offset:256
	s_waitcnt lgkmcnt(0)
	v_add_f32_e32 v32, v32, v33
	v_mov_b32_e32 v33, v32
	s_nop 1
	v_permlane32_swap_b32_e32 v33, v32
	s_and_saveexec_b64 s[40:41], s[38:39]
	s_cbranch_execz .LBB0_395
	s_waitcnt lgkmcnt(0)
	v_add_f32_e32 v32, v32, v33
	v_fma_f32 v32, v32, s80, 0.5
	v_trunc_f32_e32 v32, v32
	v_mul_f32_e32 v33, 0x2f800000, v32
	v_floor_f32_e32 v33, v33
	v_fmac_f32_e32 v32, 0xcf800000, v33
	v_cvt_u32_f32_e32 v32, v32
	v_cvt_u32_f32_e32 v33, v33
	global_atomic_add_x2 v[112:113], v[32:33], off offset:1152
; #define PG8_GAS __attribute__((address_space(1)))
; __device__ __forceinline__ unsigned cvt_pk_bf16(float lo, float hi) { unsigned r; asm volatile("v_cvt_pk_bf16_f32 %0, %1, %2" : "=v"(r) : "v"(lo), "v"(hi)); return r; }
;     __device__ __forceinline__ void operator()(const f32x4 (&acc)[2][2][4][2], const Unit& u, int wr, int wc, int fr, int fq) const {
;     ...
;             for (int m = 0; m < 4; ++m) { const int row = row0 + ai * HALF + m * 16; PG8_GAS bf16_t* rowb = XBg + (size_t)row * ldc + col0;
;                 float sq = 0.f;
; #pragma unroll
;                 for (int bj = 0; bj < 2; ++bj) { const u32x4 o = pre[ai][m][bj]; const f32x4 c0 = acc[ai][bj][m][0], c1 = acc[ai][bj][m][1];
;                     u32x4 w; w.x = cvt_pk_bf16(__uint_as_float(o.x << 16) + c0[0], __uint_as_float(o.x & 0xffff0000u) + c0[1]); w.y = cvt_pk_bf16(__uint_as_float(o.y << 16) + c0[2], __uint_as_float(o.y & 0xffff0000u) + c0[3]);
;                     w.z = cvt_pk_bf16(__uint_as_float(o.z << 16) + c1[0], __uint_as_float(o.z & 0xffff0000u) + c1[1]); w.w = cvt_pk_bf16(__uint_as_float(o.w << 16) + c1[2], __uint_as_float(o.w & 0xffff0000u) + c1[3]);
;                     *(PG8_GAS u32x4*)(rowb + bj * HALF) = w;
;                     const float a0 = __uint_as_float(w.x << 16), a1 = __uint_as_float(w.x & 0xffff0000u), a2 = __uint_as_float(w.y << 16), a3 = __uint_as_float(w.y & 0xffff0000u);
;                     const float b0 = __uint_as_float(w.z << 16), b1 = __uint_as_float(w.z & 0xffff0000u), b2 = __uint_as_float(w.w << 16), b3 = __uint_as_float(w.w & 0xffff0000u);
;                     sq += (a0 * a0 + a1 * a1) + (a2 * a2 + a3 * a3) + (b0 * b0 + b1 * b1) + (b2 * b2 + b3 * b3); }
;                 sq += __shfl_xor(sq, 16); sq += __shfl_xor(sq, 32);
;                 if (fq == 0) __hip_atomic_fetch_add(ssg + row, (unsigned long long)(sq * 1048576.0f + 0.5f), __ATOMIC_RELAXED, __HIP_MEMORY_SCOPE_AGENT); }
.LBB0_395:
	s_or_b64 exec, exec, s[40:41]
	v_lshlrev_b32_e32 v32, 16, v140
	v_add_f32_e32 v28, v28, v32
	v_and_b32_e32 v32, 0xffff0000, v140
	v_add_f32_e32 v29, v29, v32
	v_cvt_pk_bf16_f32 v28, v28, v29
	v_lshlrev_b32_e32 v29, 16, v141
	v_add_f32_e32 v29, v30, v29
	v_and_b32_e32 v30, 0xffff0000, v141
	v_add_f32_e32 v30, v31, v30
	v_cvt_pk_bf16_f32 v29, v29, v30
	v_lshlrev_b32_e32 v30, 16, v142
	v_add_f32_e32 v24, v24, v30
	v_and_b32_e32 v30, 0xffff0000, v142
	v_add_f32_e32 v25, v25, v30
	v_cvt_pk_bf16_f32 v30, v24, v25
	v_and_b32_e32 v25, 0xffff0000, v143
	v_lshlrev_b32_e32 v24, 16, v143
	v_add_f32_e32 v25, v27, v25
	v_add_f32_e32 v24, v26, v24
	v_cvt_pk_bf16_f32 v31, v24, v25
	v_and_b32_e32 v25, 0xffff0000, v28
	v_lshlrev_b32_e32 v24, 16, v28
	v_and_b32_e32 v27, 0xffff0000, v29
	v_mul_f32_e32 v25, v25, v25
	v_lshlrev_b32_e32 v26, 16, v29
	v_fmac_f32_e32 v25, v24, v24
	v_mul_f32_e32 v24, v27, v27
	global_store_dwordx4 v[210:211], v[28:31], off
	v_fmac_f32_e32 v24, v26, v26
	v_add_f32_e32 v24, v25, v24
	v_and_b32_e32 v29, 0xffff0000, v30
	v_lshlrev_b32_e32 v28, 16, v30
	v_mul_f32_e32 v25, v29, v29
	v_lshlrev_b32_e32 v30, 16, v31
	v_and_b32_e32 v31, 0xffff0000, v31
	v_fmac_f32_e32 v25, v28, v28
	v_add_f32_e32 v24, v24, v25
	v_mul_f32_e32 v25, v31, v31
	v_fmac_f32_e32 v25, v30, v30
	v_add_f32_e32 v24, v24, v25
	v_lshlrev_b32_e32 v25, 16, v128
	v_add_f32_e32 v20, v20, v25
	v_and_b32_e32 v25, 0xffff0000, v128
	v_add_f32_e32 v21, v21, v25
	v_cvt_pk_bf16_f32 v20, v20, v21
	v_lshlrev_b32_e32 v21, 16, v129
	v_add_f32_e32 v21, v22, v21
	v_and_b32_e32 v22, 0xffff0000, v129
	v_add_f32_e32 v22, v23, v22
	v_cvt_pk_bf16_f32 v21, v21, v22
	v_lshlrev_b32_e32 v22, 16, v130
	v_add_f32_e32 v16, v16, v22
	v_and_b32_e32 v22, 0xffff0000, v130
	v_add_f32_e32 v17, v17, v22
	v_cvt_pk_bf16_f32 v22, v16, v17
	v_and_b32_e32 v17, 0xffff0000, v131
	v_lshlrev_b32_e32 v16, 16, v131
	v_add_f32_e32 v17, v19, v17
	v_add_f32_e32 v16, v18, v16
	v_cvt_pk_bf16_f32 v23, v16, v17
	v_and_b32_e32 v17, 0xffff0000, v20
	v_lshlrev_b32_e32 v16, 16, v20
	v_and_b32_e32 v19, 0xffff0000, v21
	v_mul_f32_e32 v17, v17, v17
	v_lshlrev_b32_e32 v18, 16, v21
	v_fmac_f32_e32 v17, v16, v16
	v_mul_f32_e32 v16, v19, v19
	v_and_b32_e32 v26, 0xffff0000, v22
	v_fmac_f32_e32 v16, v18, v18
	v_lshlrev_b32_e32 v25, 16, v22
	v_add_f32_e32 v16, v17, v16
	v_mul_f32_e32 v17, v26, v26
	v_and_b32_e32 v28, 0xffff0000, v23
	v_fmac_f32_e32 v17, v25, v25
	v_lshlrev_b32_e32 v27, 16, v23
	v_add_f32_e32 v16, v16, v17
	v_mul_f32_e32 v17, v28, v28
	v_fmac_f32_e32 v17, v27, v27
	v_add_f32_e32 v16, v16, v17
	v_add_f32_e32 v16, v24, v16
	v_mov_b32_e32 v17, v16
	s_nop 1
	v_permlane16_swap_b32_e32 v17, v16
	global_store_dwordx4 v[210:211], v[20:23], off offset:256
	s_waitcnt lgkmcnt(0)
	v_add_f32_e32 v16, v16, v17
	v_mov_b32_e32 v17, v16
	s_nop 1
	v_permlane32_swap_b32_e32 v17, v16
	s_and_saveexec_b64 s[40:41], s[38:39]
	s_cbranch_execz .LBB0_397
	s_waitcnt lgkmcnt(0)
	v_add_f32_e32 v16, v16, v17
	v_fma_f32 v16, v16, s80, 0.5
	v_trunc_f32_e32 v16, v16
	v_mul_f32_e32 v17, 0x2f800000, v16
	v_floor_f32_e32 v17, v17
	v_fmac_f32_e32 v16, 0xcf800000, v17
	v_cvt_u32_f32_e32 v16, v16
	v_cvt_u32_f32_e32 v17, v17
	global_atomic_add_x2 v[112:113], v[16:17], off offset:1280
.LBB0_397:
	s_or_b64 exec, exec, s[40:41]
	s_waitcnt vmcnt(15)
	v_lshlrev_b32_e32 v16, 16, v132
	v_add_f32_e32 v12, v12, v16
	v_and_b32_e32 v16, 0xffff0000, v132
	v_add_f32_e32 v13, v13, v16
	v_cvt_pk_bf16_f32 v12, v12, v13
	v_lshlrev_b32_e32 v13, 16, v133
	v_add_f32_e32 v13, v14, v13
	v_and_b32_e32 v14, 0xffff0000, v133
	v_add_f32_e32 v14, v15, v14
	v_cvt_pk_bf16_f32 v13, v13, v14
	v_lshlrev_b32_e32 v14, 16, v134
	v_add_f32_e32 v8, v8, v14
	v_and_b32_e32 v14, 0xffff0000, v134
	v_add_f32_e32 v9, v9, v14
	v_cvt_pk_bf16_f32 v14, v8, v9
	v_and_b32_e32 v9, 0xffff0000, v135
	v_lshlrev_b32_e32 v8, 16, v135
	v_add_f32_e32 v9, v11, v9
	v_add_f32_e32 v8, v10, v8
	v_cvt_pk_bf16_f32 v15, v8, v9
	v_and_b32_e32 v9, 0xffff0000, v12
	v_lshlrev_b32_e32 v8, 16, v12
	v_and_b32_e32 v11, 0xffff0000, v13
	v_mul_f32_e32 v9, v9, v9
	v_lshlrev_b32_e32 v10, 16, v13
	v_fmac_f32_e32 v9, v8, v8
	v_mul_f32_e32 v8, v11, v11
	global_store_dwordx4 v[208:209], v[12:15], off
	v_fmac_f32_e32 v8, v10, v10
	v_add_f32_e32 v8, v9, v8
	v_and_b32_e32 v13, 0xffff0000, v14
	v_lshlrev_b32_e32 v12, 16, v14
	v_mul_f32_e32 v9, v13, v13
	v_lshlrev_b32_e32 v14, 16, v15
	v_and_b32_e32 v15, 0xffff0000, v15
	v_fmac_f32_e32 v9, v12, v12
	v_add_f32_e32 v8, v8, v9
	v_mul_f32_e32 v9, v15, v15
	v_fmac_f32_e32 v9, v14, v14
	v_add_f32_e32 v8, v8, v9
	s_waitcnt vmcnt(15)
	v_lshlrev_b32_e32 v9, 16, v124
	v_add_f32_e32 v4, v4, v9
	v_and_b32_e32 v9, 0xffff0000, v124
	v_add_f32_e32 v5, v5, v9
	v_cvt_pk_bf16_f32 v4, v4, v5
	v_lshlrev_b32_e32 v5, 16, v125
	v_add_f32_e32 v5, v6, v5
	v_and_b32_e32 v6, 0xffff0000, v125
	v_add_f32_e32 v6, v7, v6
	v_cvt_pk_bf16_f32 v5, v5, v6
	v_lshlrev_b32_e32 v6, 16, v126
	v_add_f32_e32 v0, v0, v6
	v_and_b32_e32 v6, 0xffff0000, v126
	v_add_f32_e32 v1, v1, v6
	v_cvt_pk_bf16_f32 v6, v0, v1
	v_and_b32_e32 v1, 0xffff0000, v127
	v_lshlrev_b32_e32 v0, 16, v127
	v_add_f32_e32 v1, v3, v1
	v_add_f32_e32 v0, v2, v0
	v_cvt_pk_bf16_f32 v7, v0, v1
	v_and_b32_e32 v1, 0xffff0000, v4
	v_lshlrev_b32_e32 v0, 16, v4
	v_and_b32_e32 v3, 0xffff0000, v5
	v_mul_f32_e32 v1, v1, v1
	v_lshlrev_b32_e32 v2, 16, v5
	v_fmac_f32_e32 v1, v0, v0
	v_mul_f32_e32 v0, v3, v3
	v_and_b32_e32 v10, 0xffff0000, v6
	v_fmac_f32_e32 v0, v2, v2
	v_lshlrev_b32_e32 v9, 16, v6
	v_add_f32_e32 v0, v1, v0
	v_mul_f32_e32 v1, v10, v10
	v_and_b32_e32 v12, 0xffff0000, v7
	v_fmac_f32_e32 v1, v9, v9
	v_lshlrev_b32_e32 v11, 16, v7
	v_add_f32_e32 v0, v0, v1
	v_mul_f32_e32 v1, v12, v12
	v_fmac_f32_e32 v1, v11, v11
	v_add_f32_e32 v0, v0, v1
	v_add_f32_e32 v0, v8, v0
	v_mov_b32_e32 v1, v0
	s_nop 1
	v_permlane16_swap_b32_e32 v1, v0
	global_store_dwordx4 v[208:209], v[4:7], off offset:256
	s_waitcnt lgkmcnt(0)
	v_add_f32_e32 v0, v0, v1
	v_mov_b32_e32 v1, v0
	s_nop 1
	v_permlane32_swap_b32_e32 v1, v0
	s_and_saveexec_b64 s[40:41], s[38:39]
	s_cbranch_execz .LBB0_399
	s_waitcnt lgkmcnt(0)
	v_add_f32_e32 v0, v0, v1
	v_fma_f32 v0, v0, s80, 0.5
	v_trunc_f32_e32 v0, v0
	v_mul_f32_e32 v1, 0x2f800000, v0
	v_floor_f32_e32 v1, v1
	v_fmac_f32_e32 v0, 0xcf800000, v1
	v_cvt_u32_f32_e32 v0, v0
	v_cvt_u32_f32_e32 v1, v1
	global_atomic_add_x2 v[112:113], v[0:1], off offset:1408
